# mixer phase s4: odd teams run hgB first and retB second, so HBM-bound retB units overlap the other half's VALU/latency-bound hgB
# baseline (speedup 1.0000x reference)
.LBB0_5:
	s_or_b64 exec, exec, s[2:3]
	s_cmp_ge_i32 s80, s81
	s_cbranch_scc1 .LBB0_487
	s_add_u32 s4, s78, 0x17024800
	s_addc_u32 s5, s79, 0
	s_add_u32 s2, s78, 0x36000
	s_addc_u32 s3, s79, 0
	s_add_u32 s8, s78, 0x3824800
	v_writelane_b32 v253, s2, 2
	s_addc_u32 s9, s79, 0
	s_movk_i32 s82, 0x161
	v_writelane_b32 v253, s3, 3
	s_add_u32 s2, s78, 0x39000
	s_addc_u32 s3, s79, 0
	s_lshl_b32 s61, s62, 3
	s_mov_b32 s100, 0
	v_writelane_b32 v255, s100, 47
	v_writelane_b32 v255, s100, 48
	v_writelane_b32 v255, s100, 49
	s_add_u32 s38, s0, 0x88
	s_addc_u32 s39, s1, 0
	s_add_u32 s58, s78, 0x4000
	s_addc_u32 s59, s79, 0
	v_writelane_b32 v253, s2, 4
	s_cmpk_lt_i32 s62, 0xc0
	v_lshrrev_b32_e32 v1, 20, v0
	v_writelane_b32 v253, s3, 5
	s_cselect_b64 s[2:3], -1, 0
	v_writelane_b32 v253, s2, 6
	s_cmp_eq_u32 s62, 0
	v_lshrrev_b32_e32 v0, 10, v0
	v_writelane_b32 v253, s3, 7
	s_cselect_b64 s[2:3], -1, 0
	v_writelane_b32 v253, s2, 8
	v_or_b32_e32 v0, v0, v1
	s_load_dwordx16 s[40:55], s[0:1], 0x0
	v_writelane_b32 v253, s3, 9
	s_add_u32 s2, s78, 0x64000
	s_addc_u32 s3, s79, 0
	s_add_u32 s22, s78, 0x7824800
	v_writelane_b32 v253, s2, 10
	s_addc_u32 s23, s79, 0
	s_mov_b32 s97, 0
	v_writelane_b32 v253, s3, 11
	s_add_u32 s2, s78, 0x2d24800
	s_addc_u32 s3, s79, 0
	v_writelane_b32 v253, s2, 12
	s_cmpk_lt_i32 s62, 0x200
	v_mbcnt_lo_u32_b32 v1, -1, 0
	v_writelane_b32 v253, s3, 13
	s_cselect_b64 s[2:3], -1, 0
	v_writelane_b32 v253, s2, 14
	s_ashr_i32 s63, s62, 31
	s_mov_b32 s98, s97
	v_writelane_b32 v253, s3, 15
	s_lshr_b32 s2, s63, 29
	s_add_i32 s3, s62, s2
	s_ashr_i32 s2, s3, 3
	s_and_b32 s3, s3, -8
	s_sub_i32 s3, s62, s3
	s_lshl_b32 s7, s3, 6
	s_add_u32 s10, s78, 0x1724800
	s_addc_u32 s11, s79, 0
	v_writelane_b32 v253, s10, 16
	s_cmpk_lt_i32 s62, 0xb00
	s_mov_b32 s99, s97
	v_writelane_b32 v253, s11, 17
	s_cselect_b64 s[10:11], -1, 0
	v_writelane_b32 v253, s10, 18
	v_mbcnt_hi_u32_b32 v204, -1, v1
	s_mov_b32 s96, s97
	v_writelane_b32 v253, s11, 19
	s_lshl_b32 s10, s3, 8
	s_cmp_lt_i32 s3, 0
	s_cselect_b32 s12, s82, 0x160
	s_mul_i32 s11, s3, 0x41
	s_mul_i32 s12, s12, s3
	s_mulk_i32 s3, 0x101
	s_cselect_b32 s7, s11, s7
	s_cselect_b32 s3, s3, s10
	s_add_i32 s12, s12, s2
	s_mul_hi_i32 s10, s12, 0x2e8ba2e9
	s_lshr_b32 s11, s10, 31
	s_ashr_i32 s10, s10, 5
	s_add_i32 s10, s10, s11
	s_mul_i32 s11, s10, 0xb0
	s_sub_i32 s11, s12, s11
	s_lshl_b32 s13, s10, 3
	s_bfe_u32 s10, s11, 0x3001c
	s_add_i32 s12, s11, s10
	s_sext_i32_i16 s14, s12
	s_and_b32 s12, s12, 0xfff8
	s_sub_i32 s11, s11, s12
	s_sext_i32_i16 s11, s11
	s_ashr_i32 s12, s14, 3
	s_add_i32 s11, s13, s11
	v_writelane_b32 v253, s12, 20
	s_lshr_b32 s10, s14, 3
	v_writelane_b32 v253, s11, 21
	s_ashr_i32 s11, s11, 31
	v_writelane_b32 v253, s11, 22
	s_bfe_i64 s[10:11], s[10:11], 0x100000
	v_writelane_b32 v253, s10, 23
	v_mov_b64_e32 v[242:243], s[98:99]
	v_and_b32_e32 v1, 64, v204
	v_writelane_b32 v253, s11, 24
	s_add_u32 s10, s78, 0x1324800
	s_addc_u32 s11, s79, 0
	v_writelane_b32 v253, s10, 25
	s_cmpk_lt_i32 s62, 0x600
	v_mov_b32_e32 v129, 0
	v_writelane_b32 v253, s11, 26
	s_cselect_b64 s[10:11], -1, 0
	v_writelane_b32 v253, s10, 27
	v_mov_b32_e32 v201, 0x358637bd
	v_mov_b32_e32 v202, 0x3ecc95a3
	v_writelane_b32 v253, s11, 28
	s_ashr_i32 s10, s62, 5
	s_mul_hi_i32 s11, s10, 0x2aaaaaab
	s_lshr_b32 s12, s11, 31
	s_add_i32 s11, s11, s12
	s_mul_i32 s12, s11, 6
	s_sub_i32 s10, s10, s12
	s_lshl_b32 s12, s62, 7
	s_lshl_b32 s11, s11, 12
	v_writelane_b32 v253, s12, 29
	s_and_b32 s12, s12, 0xf80
	s_lshl_b32 s10, s10, 6
	s_or_b32 s88, s11, s12
	s_ashr_i32 s11, s10, 31
	s_lshl_b64 s[10:11], s[10:11], 1
	s_add_u32 s10, s22, s10
	s_addc_u32 s11, s23, s11
	v_writelane_b32 v253, s10, 30
	s_add_u32 s12, s78, 0x1b824800
	s_addc_u32 s13, s79, 0
	v_writelane_b32 v253, s11, 31
	s_lshl_b64 s[10:11], s[62:63], 14
	s_add_u32 s10, s12, s10
	v_writelane_b32 v253, s12, 32
	s_addc_u32 s11, s13, s11
	v_mov_b64_e32 v[240:241], s[96:97]
	v_writelane_b32 v253, s13, 33
	s_add_u32 s12, s10, 0x2000
	v_writelane_b32 v253, s10, 34
	s_addc_u32 s13, s11, 0
	s_cmpk_lt_i32 s62, 0x100
	v_writelane_b32 v253, s11, 35
	v_writelane_b32 v253, s12, 36
	s_cselect_b64 s[10:11], -1, 0
	v_mov_b32_e32 v203, 1
	v_writelane_b32 v253, s13, 37
	v_writelane_b32 v253, s10, 38
	v_add_u32_e32 v205, 64, v1
	v_xor_b32_e32 v206, 1, v204
	v_writelane_b32 v253, s11, 39
	s_add_u32 s10, s78, 0x1d024800
	s_addc_u32 s11, s79, 0
	v_writelane_b32 v253, s10, 40
	v_xor_b32_e32 v207, 2, v204
	v_xor_b32_e32 v252, 4, v204
	v_writelane_b32 v253, s11, 41
	s_add_u32 s10, s78, 0xe4800
	s_addc_u32 s11, s79, 0
	s_lshl_b32 s89, s62, 9
	s_add_u32 s30, s78, 0x64800
	s_addc_u32 s31, s79, 0
	s_add_i32 s91, s89, 0xffff4000
	s_add_i32 s12, s61, 0xd40
	v_writelane_b32 v253, s12, 42
	s_add_u32 s12, s78, 0x324800
	s_addc_u32 s13, s79, 0
	v_writelane_b32 v253, s12, 43
	v_xor_b32_e32 v210, 16, v204
	v_xor_b32_e32 v211, 32, v204
	v_writelane_b32 v253, s13, 44
	s_and_b32 s12, s62, 7
	s_xor_b32 s13, s12, 7
	s_cmpk_lt_u32 s62, 0x900
	v_writelane_b32 v253, s13, 45
	s_cselect_b64 s[14:15], -1, 0
	v_writelane_b32 v253, s14, 46
	s_lshl_b32 s92, s12, 6
	v_mov_b64_e32 v[130:131], 0x200
	v_writelane_b32 v253, s15, 47
	s_lshr_b32 s15, s62, 3
	s_mul_i32 s13, s15, 0xaaab
	s_lshr_b32 s13, s13, 21
	s_mul_i32 s14, s13, 0xffffffd0
	s_lshl_b32 s13, s13, 9
	s_add_i32 s14, s14, s15
	s_or_b32 s12, s13, s92
	s_or_b32 s12, s12, s14
	s_ashr_i32 s12, s12, 6
	s_lshr_b32 s14, s14, 3
	s_mul_hi_i32 s13, s12, 0x2aaaaaab
	s_and_b32 s17, s14, 6
	v_writelane_b32 v253, s15, 48
	s_lshr_b32 s15, s13, 31
	s_lshr_b32 s16, 16, s17
	s_add_i32 s13, s13, s15
	s_bfe_u32 s14, s62, 0x40003
	s_sub_i32 s15, 4, s17
	s_add_i32 s16, s16, -1
	s_lshr_b32 s15, s14, s15
	s_and_b32 s14, s16, s14
	s_lshl_b32 s16, s13, 12
	s_or_b32 s15, s16, s15
	s_mul_i32 s13, s13, 6
	v_writelane_b32 v253, s15, 49
	s_sub_i32 s12, s12, s13
	s_lshl_b32 s12, s12, 6
	v_writelane_b32 v253, s17, 50
	s_lshr_b32 s15, 0x1000, s17
	s_lshl_b32 s14, s14, 8
	s_ashr_i32 s13, s12, 31
	v_writelane_b32 v253, s15, 51
	s_lshl_b64 s[12:13], s[12:13], 1
	v_writelane_b32 v253, s14, 52
	s_sub_i32 s14, s14, 64
	s_add_u32 s12, s22, s12
	v_writelane_b32 v253, s14, 53
	s_addc_u32 s13, s23, s13
	v_writelane_b32 v253, s12, 54
	s_cmpk_lt_i32 s62, 0x400
	v_mov_b64_e32 v[132:133], 0x1ff
	v_writelane_b32 v253, s13, 55
	s_cselect_b64 s[12:13], -1, 0
	v_writelane_b32 v253, s12, 56
	s_cmpk_lt_i32 s62, 0x800
	v_mov_b32_e32 v212, 0x42800000
	v_writelane_b32 v253, s13, 57
	s_cselect_b64 s[12:13], -1, 0
	v_writelane_b32 v253, s12, 58
	s_cmp_lt_i32 s81, 21
	v_mov_b32_e32 v213, 0x7fc00000
	v_writelane_b32 v253, s13, 59
	s_cselect_b64 s[12:13], -1, 0
	v_writelane_b32 v253, s12, 60
	v_mov_b32_e32 v214, 0xff800000
	v_mov_b32_e32 v215, 0x41f00000
	v_writelane_b32 v253, s13, 61
	s_add_u32 s12, s78, 0x200
	s_addc_u32 s13, s79, 0
	v_writelane_b32 v253, s12, 62
	v_mov_b32_e32 v216, 0x1f00
	v_mov_b32_e32 v217, 6
	v_writelane_b32 v253, s13, 63
	s_add_u32 s12, s78, 0x1000
	s_addc_u32 s13, s79, 0
	v_writelane_b32 v254, s12, 0
	v_mov_b32_e32 v134, 0x3e38aa3b
	v_mov_b32_e32 v218, 0xf149f2ca
	v_writelane_b32 v254, s13, 1
	s_add_u32 s12, s78, 0x1100
	s_addc_u32 s13, s79, 0
	v_writelane_b32 v254, s12, 2
	v_mov_b32_e32 v136, 0x3f317218
	v_mov_b64_e32 v[138:139], 0x7ff
	v_writelane_b32 v254, s13, 3
	s_add_u32 s12, s78, 0x1200
	s_addc_u32 s13, s79, 0
	v_writelane_b32 v254, s12, 4
	v_mov_b32_e32 v219, 0x3f7fffef
	s_mov_b32 s95, 0x2aaaaaab
	v_writelane_b32 v254, s13, 5
	s_add_u32 s12, s78, 0x1300
	s_addc_u32 s13, s79, 0
	v_writelane_b32 v254, s12, 6
	s_cmp_eq_u32 s6, 15
	s_movk_i32 s94, 0xf80
	v_writelane_b32 v254, s13, 7
	s_cselect_b64 s[12:13], -1, 0
	v_writelane_b32 v254, s12, 8
	s_cmp_eq_u32 s6, 14
	s_movk_i32 s86, 0x1000
	v_writelane_b32 v254, s13, 9
	s_cselect_b64 s[12:13], -1, 0
	v_writelane_b32 v254, s12, 10
	s_cmp_eq_u32 s6, 13
	s_movk_i32 s84, 0x6000
	v_writelane_b32 v254, s13, 11
	s_cselect_b64 s[12:13], -1, 0
	v_writelane_b32 v254, s12, 12
	s_cmp_eq_u32 s6, 12
	s_mov_b32 s60, 0xec801000
	v_writelane_b32 v254, s13, 13
	s_cselect_b64 s[12:13], -1, 0
	v_writelane_b32 v254, s12, 14
	s_cmp_eq_u32 s6, 11
	s_mov_b32 s33, 0xc000
	v_writelane_b32 v254, s13, 15
	s_cselect_b64 s[12:13], -1, 0
	v_writelane_b32 v254, s12, 16
	s_cmp_eq_u32 s6, 10
	s_movk_i32 s93, 0x1f00
	v_writelane_b32 v254, s13, 17
	s_cselect_b64 s[12:13], -1, 0
	v_writelane_b32 v254, s12, 18
	s_cmp_eq_u32 s6, 9
	s_mov_b32 s85, 0xc1f00000
	v_writelane_b32 v254, s13, 19
	s_cselect_b64 s[12:13], -1, 0
	v_writelane_b32 v254, s12, 20
	s_cmp_eq_u32 s6, 8
	s_mov_b32 s90, 0xc0000
	v_writelane_b32 v254, s13, 21
	s_cselect_b64 s[12:13], -1, 0
	v_writelane_b32 v254, s12, 22
	s_cmp_eq_u32 s6, 7
	s_mov_b32 s87, 0x180000
	v_writelane_b32 v254, s13, 23
	s_cselect_b64 s[12:13], -1, 0
	v_writelane_b32 v254, s12, 24
	s_cmp_eq_u32 s6, 6
	s_movk_i32 s83, 0x300
	v_writelane_b32 v254, s13, 25
	s_cselect_b64 s[12:13], -1, 0
	v_writelane_b32 v254, s12, 26
	s_cmp_eq_u32 s6, 5
	s_mov_b64 s[98:99], 0x80
	v_writelane_b32 v254, s13, 27
	s_cselect_b64 s[12:13], -1, 0
	v_writelane_b32 v254, s12, 28
	s_cmp_eq_u32 s6, 4
	s_mov_b32 s18, 0x3e38aa3b
	v_writelane_b32 v254, s13, 29
	s_cselect_b64 s[12:13], -1, 0
	v_writelane_b32 v254, s12, 30
	s_cmp_eq_u32 s6, 3
	s_nop 0
	v_writelane_b32 v254, s13, 31
	s_cselect_b64 s[12:13], -1, 0
	v_writelane_b32 v254, s12, 32
	s_cmp_eq_u32 s6, 2
	s_nop 0
	v_writelane_b32 v254, s13, 33
	s_cselect_b64 s[12:13], -1, 0
	v_writelane_b32 v254, s12, 34
	s_cmp_eq_u32 s6, 1
	s_nop 0
	v_writelane_b32 v254, s13, 35
	s_cselect_b64 s[12:13], -1, 0
	v_writelane_b32 v254, s12, 36
	s_cmp_eq_u32 s6, 0
	s_nop 0
	v_writelane_b32 v254, s13, 37
	s_cselect_b64 s[12:13], -1, 0
	s_lshl_b32 s6, s6, 8
	v_writelane_b32 v254, s12, 38
	s_add_u32 s6, s78, s6
	s_nop 0
	v_writelane_b32 v254, s13, 39
	s_addc_u32 s12, s79, 0
	s_add_u32 s14, s6, 0x1400
	s_addc_u32 s15, s12, 0
	v_writelane_b32 v254, s14, 40
	s_nop 1
	v_writelane_b32 v254, s15, 41
	s_add_u32 s14, s6, 0x2400
	s_addc_u32 s15, s12, 0
	v_writelane_b32 v254, s14, 42
	s_add_u32 s12, s78, 0x3400
	s_addc_u32 s13, s79, 0
	v_writelane_b32 v254, s15, 43
	v_writelane_b32 v254, s12, 44
	s_nop 1
	v_writelane_b32 v254, s13, 45
	s_add_u32 s12, s78, 0x3500
	s_addc_u32 s13, s79, 0
	s_add_i32 s6, s7, s2
	s_ashr_i32 s7, s6, 31
	s_lshr_b32 s7, s7, 27
	v_writelane_b32 v254, s12, 46
	s_add_i32 s7, s6, s7
	s_add_i32 s2, s3, s2
	v_writelane_b32 v254, s13, 47
	s_and_b32 s12, s7, 0xffe0
	s_sub_i32 s6, s6, s12
	s_bfe_i32 s12, s6, 0x80000
	s_bfe_u32 s12, s12, 0x3000c
	s_add_i32 s12, s6, s12
	s_and_b32 s13, s12, 0xf8
	s_ashr_i32 s3, s2, 31
	s_sub_i32 s6, s6, s13
	s_ashr_i32 s7, s7, 5
	s_lshr_b32 s3, s3, 25
	s_lshl_b32 s7, s7, 3
	s_sext_i32_i8 s6, s6
	s_add_i32 s3, s2, s3
	s_add_i32 s13, s7, s6
	s_and_b32 s6, s3, 0xff80
	s_sub_i32 s2, s2, s6
	s_bfe_i32 s6, s2, 0x80000
	s_bfe_u32 s6, s6, 0x3000c
	s_add_i32 s6, s2, s6
	s_and_b32 s7, s6, 0xf8
	s_sub_i32 s2, s2, s7
	s_ashr_i32 s3, s3, 7
	s_lshl_b32 s3, s3, 3
	s_sext_i32_i8 s2, s2
	s_add_i32 s7, s3, s2
	s_movk_i32 s2, 0x3ff
	v_and_or_b32 v0, v0, s2, v200
	s_bfe_i32 s2, s12, 0x80000
	s_sext_i32_i16 s2, s2
	s_bfe_i32 s3, s6, 0x80000
	s_sext_i32_i16 s3, s3
	s_ashr_i32 s6, s2, 3
	s_lshr_b32 s2, s2, 3
	v_writelane_b32 v254, s6, 48
	s_bfe_i64 s[14:15], s[2:3], 0x100000
	v_writelane_b32 v254, s14, 49
	s_ashr_i32 s2, s3, 3
	s_nop 0
	v_writelane_b32 v254, s15, 50
	v_writelane_b32 v254, s2, 51
	s_lshr_b32 s2, s3, 3
	s_bfe_i64 s[2:3], s[2:3], 0x100000
	v_writelane_b32 v254, s2, 52
	s_nop 1
	v_writelane_b32 v254, s3, 53
	v_writelane_b32 v254, s13, 54
	s_ashr_i32 s2, s13, 31
	v_writelane_b32 v254, s2, 55
	v_writelane_b32 v254, s7, 56
	s_ashr_i32 s2, s7, 31
	v_writelane_b32 v254, s2, 57
	s_add_u32 s2, s76, 0xc00
	s_addc_u32 s3, s77, 0
	v_writelane_b32 v254, s2, 58
	s_nop 1
	v_writelane_b32 v254, s3, 59
	s_lshl_b32 s2, s62, 5
	v_writelane_b32 v254, s2, 60
	s_waitcnt lgkmcnt(0)
	s_add_u32 s0, s40, 0xc00
	v_writelane_b32 v254, s40, 61
	s_addc_u32 s1, s41, 0
	s_nop 0
	v_writelane_b32 v255, s43, 0
	v_writelane_b32 v255, s44, 1
	v_writelane_b32 v255, s45, 2
	v_writelane_b32 v255, s46, 3
	v_writelane_b32 v255, s47, 4
	v_writelane_b32 v255, s48, 5
	v_writelane_b32 v255, s49, 6
	v_writelane_b32 v255, s50, 7
	v_writelane_b32 v255, s51, 8
	v_writelane_b32 v255, s52, 9
	v_writelane_b32 v255, s53, 10
	v_writelane_b32 v255, s54, 11
	v_writelane_b32 v255, s55, 12
	v_writelane_b32 v255, s0, 13
	v_writelane_b32 v254, s41, 62
	v_writelane_b32 v254, s42, 63
	v_writelane_b32 v255, s1, 14
	s_add_i32 s0, 16, 0x4800
	v_writelane_b32 v255, s0, 15
	v_cmp_eq_u32_e64 s[0:1], 0, v0
	s_nop 1
	v_writelane_b32 v255, s0, 16
	s_nop 1
	v_writelane_b32 v255, s1, 17
	v_writelane_b32 v255, s38, 18
	s_nop 1
	v_writelane_b32 v255, s39, 19
	v_writelane_b32 v255, s58, 20
	s_nop 1
	v_writelane_b32 v255, s59, 21
	v_writelane_b32 v255, s92, 22
	s_branch .LBB0_11

.Ls4_retb:
	v_readlane_b32 s2, v255, 49
	s_cmp_lg_u32 s2, 0
	s_cbranch_scc1 .Ls4_cont
	s_bitcmp1_b32 s61, 6
	s_cbranch_scc0 .Ls4_cont
	s_mov_b32 s2, 1
	v_writelane_b32 v255, s2, 49
	s_branch .LBB0_188
.Ls4_cont:
	v_readlane_b32 s0, v253, 27
	v_mov_b32_e32 v24, v200
	v_readlane_b32 s1, v253, 28
	s_andn2_b64 vcc, exec, s[0:1]
	v_readfirstlane_b32 s2, v24
	s_cbranch_vccnz .LBB0_188
	v_readlane_b32 s6, v253, 30
	v_ashrrev_i32_e32 v112, 2, v24
	v_readlane_b32 s7, v253, 31
	s_waitcnt vmcnt(0)
	v_add_u32_e32 v0, s88, v112
	v_lshlrev_b32_e32 v31, 3, v24
	v_mov_b64_e32 v[26:27], s[6:7]
	v_mad_i64_i32 v[0:1], s[6:7], v0, s93, v[26:27]
	v_and_b32_e32 v76, 0xffffffc0, v31
	v_ashrrev_i32_e32 v77, 31, v76
	v_readlane_b32 s6, v253, 34
	v_lshlrev_b64 v[16:17], 1, v[76:77]
	v_readlane_b32 s7, v253, 35
	v_and_b32_e32 v30, 56, v31
	v_lshlrev_b32_e32 v32, 1, v30
	v_lshl_add_u64 v[18:19], s[6:7], 0, v[16:17]
	v_readlane_b32 s6, v253, 36
	v_readlane_b32 s7, v253, 37
	v_mov_b32_e32 v33, v129
	v_lshl_add_u64 v[18:19], v[18:19], 0, v[32:33]
	v_lshl_add_u64 v[16:17], s[6:7], 0, v[16:17]
	v_lshl_add_u64 v[20:21], v[16:17], 0, v[32:33]
	v_and_b32_e32 v33, -16, v112
	v_and_b32_e32 v25, 15, v24
	v_lshlrev_b32_e32 v2, 4, v24
	v_add_u32_e32 v33, s88, v33
	v_and_b32_e32 v28, 48, v2
	v_or_b32_e32 v33, v33, v25
	v_lshlrev_b32_e32 v128, 1, v28
	v_mad_i64_i32 v[26:27], s[6:7], v33, s93, v[26:27]
	v_lshrrev_b32_e32 v33, 1, v24
	v_lshl_add_u64 v[12:13], v[0:1], 0, v[128:129]
	v_and_b32_e32 v34, 24, v33
	global_load_dwordx4 v[0:3], v[12:13], off offset:3088
	global_load_dwordx4 v[4:7], v[12:13], off offset:3072
	global_load_dwordx4 v[8:11], v[12:13], off offset:3856
	s_nop 0
	global_load_dwordx4 v[12:15], v[12:13], off offset:3840
	v_lshlrev_b32_e32 v36, 1, v34
	v_mov_b32_e32 v37, v129
	v_lshl_add_u64 v[26:27], v[26:27], 0, v[36:37]
	global_load_dwordx4 v[16:19], v[18:19], off
	s_nop 0
	global_load_dwordx4 v[20:23], v[20:21], off
	s_nop 0
	global_load_dwordx4 v[68:71], v[26:27], off offset:2304
	global_load_dwordx4 v[64:67], v[26:27], off offset:2368
	v_readlane_b32 s0, v255, 31
	v_readlane_b32 s1, v255, 32
	s_mulk_i32 s0, 0x180
	s_ashr_i32 s1, s0, 31
	v_readlane_b32 s40, v254, 61
	s_lshl_b64 s[0:1], s[0:1], 2
	v_readlane_b32 s52, v255, 9
	v_readlane_b32 s53, v255, 10
	s_add_u32 s0, s52, s0
	v_lshrrev_b32_e32 v26, 3, v24
	s_movk_i32 s3, 0x90
	s_addc_u32 s1, s53, s1
	v_bfe_u32 v29, v24, 4, 2
	v_mul_lo_u32 v26, v26, s3
	s_ashr_i32 s2, s2, 2
	v_add3_u32 v115, 16, v32, v26
	v_bfi_b32 v116, -16, s2, v24
	v_lshlrev_b32_e32 v26, 2, v29
	v_sub_u32_e32 v32, v116, v26
	v_sub_u32_e32 v33, 0, v32
	v_max_i32_e32 v33, v32, v33
	v_cvt_f32_u32_e32 v121, v33
	v_xad_u32 v33, v26, -1, v116
	v_sub_u32_e32 v35, 0, v33
	v_max_i32_e32 v33, v33, v35
	v_cvt_f32_u32_e32 v122, v33
	v_add_u32_e32 v33, -2, v32
	v_sub_u32_e32 v35, 2, v32
	v_max_i32_e32 v33, v33, v35
	v_cvt_f32_u32_e32 v123, v33
	v_add_u32_e32 v33, -3, v32
	v_sub_u32_e32 v35, 3, v32
	v_max_i32_e32 v33, v33, v35
	v_cvt_f32_u32_e32 v124, v33
	v_add_u32_e32 v33, -16, v32
	v_sub_u32_e32 v35, 16, v32
	v_max_i32_e32 v33, v33, v35
	v_cvt_f32_u32_e32 v125, v33
	v_subrev_u32_e32 v33, 17, v32
	v_sub_u32_e32 v35, 17, v32
	v_max_i32_e32 v33, v33, v35
	v_cvt_f32_u32_e32 v126, v33
	v_subrev_u32_e32 v33, 18, v32
	v_sub_u32_e32 v35, 18, v32
	v_max_i32_e32 v33, v33, v35
	v_cvt_f32_u32_e32 v127, v33
	v_subrev_u32_e32 v33, 19, v32
	v_sub_u32_e32 v35, 19, v32
	v_max_i32_e32 v33, v33, v35
	v_cvt_f32_u32_e32 v135, v33
	v_subrev_u32_e32 v33, 32, v32
	v_sub_u32_e32 v35, 32, v32
	v_max_i32_e32 v33, v33, v35
	v_cvt_f32_u32_e32 v137, v33
	v_subrev_u32_e32 v33, 33, v32
	v_sub_u32_e32 v35, 33, v32
	v_max_i32_e32 v33, v33, v35
	v_cvt_f32_u32_e32 v140, v33
	v_subrev_u32_e32 v33, 34, v32
	v_sub_u32_e32 v35, 34, v32
	v_max_i32_e32 v33, v33, v35
	v_cvt_f32_u32_e32 v141, v33
	v_subrev_u32_e32 v33, 35, v32
	v_sub_u32_e32 v35, 35, v32
	v_max_i32_e32 v33, v33, v35
	v_cvt_f32_u32_e32 v142, v33
	v_subrev_u32_e32 v33, 48, v32
	v_sub_u32_e32 v35, 48, v32
	v_max_i32_e32 v33, v33, v35
	v_cvt_f32_u32_e32 v143, v33
	v_subrev_u32_e32 v33, 49, v32
	v_sub_u32_e32 v35, 49, v32
	v_max_i32_e32 v33, v33, v35
	v_cvt_f32_u32_e32 v144, v33
	v_subrev_u32_e32 v33, 50, v32
	v_sub_u32_e32 v35, 50, v32
	v_max_i32_e32 v33, v33, v35
	v_cvt_f32_u32_e32 v145, v33
	v_subrev_u32_e32 v33, 51, v32
	v_sub_u32_e32 v35, 51, v32
	v_max_i32_e32 v33, v33, v35
	v_cvt_f32_u32_e32 v146, v33
	v_subrev_u32_e32 v33, 64, v32
	v_sub_u32_e32 v35, 64, v32
	v_max_i32_e32 v33, v33, v35
	v_cvt_f32_u32_e32 v147, v33
	v_add_u32_e32 v33, 0xffffffbf, v32
	v_sub_u32_e32 v35, 0x41, v32
	v_max_i32_e32 v33, v33, v35
	v_cvt_f32_u32_e32 v148, v33
	v_add_u32_e32 v33, 0xffffffbe, v32
	v_sub_u32_e32 v35, 0x42, v32
	v_max_i32_e32 v33, v33, v35
	v_cvt_f32_u32_e32 v149, v33
	v_add_u32_e32 v33, 0xffffffbd, v32
	v_sub_u32_e32 v35, 0x43, v32
	v_max_i32_e32 v33, v33, v35
	v_cvt_f32_u32_e32 v150, v33
	v_add_u32_e32 v33, 0xffffffb0, v32
	v_sub_u32_e32 v35, 0x50, v32
	v_max_i32_e32 v33, v33, v35
	v_cvt_f32_u32_e32 v151, v33
	v_add_u32_e32 v33, 0xffffffaf, v32
	v_sub_u32_e32 v35, 0x51, v32
	v_max_i32_e32 v33, v33, v35
	v_cvt_f32_u32_e32 v152, v33
	v_add_u32_e32 v33, 0xffffffae, v32
	v_sub_u32_e32 v35, 0x52, v32
	v_max_i32_e32 v33, v33, v35
	v_cvt_f32_u32_e32 v153, v33
	v_add_u32_e32 v33, 0xffffffad, v32
	v_sub_u32_e32 v35, 0x53, v32
	v_max_i32_e32 v33, v33, v35
	v_cvt_f32_u32_e32 v154, v33
	v_add_u32_e32 v33, 0xffffffa0, v32
	v_sub_u32_e32 v35, 0x60, v32
	v_max_i32_e32 v33, v33, v35
	v_cvt_f32_u32_e32 v155, v33
	v_add_u32_e32 v33, 0xffffff9f, v32
	v_sub_u32_e32 v35, 0x61, v32
	v_max_i32_e32 v33, v33, v35
	v_cvt_f32_u32_e32 v156, v33
	v_add_u32_e32 v33, 0xffffff9e, v32
	v_sub_u32_e32 v35, 0x62, v32
	v_max_i32_e32 v33, v33, v35
	v_cvt_f32_u32_e32 v157, v33
	v_add_u32_e32 v33, 0xffffff9d, v32
	v_sub_u32_e32 v35, 0x63, v32
	v_max_i32_e32 v33, v33, v35
	v_cvt_f32_u32_e32 v158, v33
	v_add_u32_e32 v33, 0xffffff90, v32
	v_sub_u32_e32 v35, 0x70, v32
	v_max_i32_e32 v33, v33, v35
	v_cvt_f32_u32_e32 v159, v33
	v_add_u32_e32 v33, 0xffffff8f, v32
	v_sub_u32_e32 v35, 0x71, v32
	v_max_i32_e32 v33, v33, v35
	v_cvt_f32_u32_e32 v160, v33
	v_add_u32_e32 v33, 0xffffff8e, v32
	v_sub_u32_e32 v35, 0x72, v32
	v_mul_lo_u32 v27, v112, s3
	v_max_i32_e32 v33, v33, v35
	v_add3_u32 v114, 16, v128, v27
	s_load_dword s12, s[38:39], 0x0
	v_add_u32_e32 v27, 1, v116
	v_cvt_f32_u32_e32 v161, v33
	v_add_u32_e32 v33, 0xffffff8d, v32
	v_sub_u32_e32 v32, 0x73, v32
	v_cvt_f32_i32_e32 v117, v27
	v_sub_u32_e32 v27, 0x80, v116
	v_cmp_lt_i32_e32 vcc, v210, v205
	v_max_i32_e32 v32, v33, v32
	v_bfi_b32 v113, -16, v112, v24
	v_cvt_f32_i32_e32 v118, v27
	v_lshlrev_b32_e32 v128, 4, v29
	v_bfe_u32 v24, v24, 2, 2
	v_and_b32_e32 v29, 24, v31
	v_cndmask_b32_e32 v31, v204, v210, vcc
	v_cmp_lt_i32_e32 vcc, v211, v205
	v_cvt_f32_u32_e32 v162, v32
	v_or_b32_e32 v24, v26, v24
	v_lshlrev_b32_e32 v119, 2, v31
	v_cndmask_b32_e32 v31, v204, v211, vcc
	v_add_u32_e32 v27, 16, v128
	v_add_u32_e32 v29, 16, v29
	v_lshlrev_b32_e32 v120, 2, v31
	v_mul_u32_u24_e32 v31, 0x90, v25
	v_mul_u32_u24_e32 v24, 0x90, v24
	v_mul_u32_u24_e32 v25, 0x48, v25
	v_lshl_add_u32 v163, v25, 1, v27
	v_lshl_add_u64 v[78:79], s[0:1], 0, v[128:129]
	s_waitcnt lgkmcnt(0)
	s_lshl_b32 s13, s12, 7
	v_lshlrev_b32_e32 v80, 1, v28
	v_lshlrev_b32_e32 v82, 1, v30
	v_lshlrev_b32_e32 v84, 1, v34
	v_lshlrev_b32_e32 v128, 1, v26
	v_add_u32_e32 v164, v27, v31
	v_add_u32_e32 v165, v29, v24
	v_readlane_b32 s15, v253, 29
	s_mov_b32 s0, s62
	v_readlane_b32 s41, v254, 62
	v_readlane_b32 s42, v254, 63
	v_readlane_b32 s43, v255, 0
	v_readlane_b32 s44, v255, 1
	v_readlane_b32 s45, v255, 2
	v_readlane_b32 s46, v255, 3
	v_readlane_b32 s47, v255, 4
	v_readlane_b32 s48, v255, 5
	v_readlane_b32 s49, v255, 6
	v_readlane_b32 s50, v255, 7
	v_readlane_b32 s51, v255, 8
	v_readlane_b32 s54, v255, 11
	v_readlane_b32 s55, v255, 12
	s_branch .LBB0_184

.LBB0_188:
	v_readlane_b32 s0, v255, 49
	s_cmp_eq_u32 s0, 2
	s_cbranch_scc0 .Ls4_hgb
	s_mov_b32 s0, 0
	v_writelane_b32 v255, s0, 49
	s_branch .LBB0_203

.LBB0_203:
	v_readlane_b32 s2, v255, 49
	s_cmp_eq_u32 s2, 1
	s_cbranch_scc0 .Ls4_join
	s_mov_b32 s2, 2
	v_writelane_b32 v255, s2, 49
	v_readlane_b32 s38, v255, 18
	v_readlane_b32 s39, v255, 19
	s_mov_b32 s96, 0xc2fc0000
	s_barrier
	s_branch .Ls4_retb
